# grid barrier: arrival ticket issued ahead of the L1 invalidate; the ticket wait leaves the invalidate in flight
# baseline (speedup 1.0000x reference)
; DI unsigned xb_add(unsigned* p, unsigned v) { return __hip_atomic_fetch_add(p, v, __ATOMIC_RELAXED, __HIP_MEMORY_SCOPE_AGENT); }
; DI void xcd_barrier(const XcdBarrier& b) {
;     ...
;     unsigned long long ba_ = (unsigned long long)b.bar; unsigned bx = b.x; asm volatile("" : "+v"(bx));
;     unsigned* bar = (unsigned*)ba_;
;     __builtin_amdgcn_s_waitcnt(0);
;     unsigned nloc = b.st[0], nx = b.st[1];
;     if (nloc == 0u) { xcd_barrier_complete(bar, bx, nloc, nx); b.st[0] = nloc; b.st[1] = nx; }
;     const unsigned old = xb_add(&bar[XB_XSUB(bx)], 1u);
;     const unsigned gen = old / nloc;
;     if (old + 1u == (gen + 1u) * nloc) {
.LBB0_187:
	v_lshlrev_b32_e32 v4, 6, v1
	v_readlane_b32 s2, v249, 48
	v_add_u32_e32 v2, 0x500, v4
	v_mov_b32_e32 v3, 0
	v_readlane_b32 s3, v249, 49
	v_mov_b32_e32 v1, 1
	s_nop 0
	v_lshl_add_u64 v[6:7], v[2:3], 2, s[2:3]
	global_atomic_add v1, v[6:7], v1, off sc0
	buffer_inv sc1
	v_cvt_f32_u32_e32 v2, v0
	v_sub_u32_e32 v6, 0, v0
	v_rcp_iflag_f32_e32 v2, v2
	s_nop 0
	v_mul_f32_e32 v2, 0x4f7ffffe, v2
	v_cvt_u32_f32_e32 v2, v2
	v_mul_lo_u32 v6, v6, v2
	v_mul_hi_u32 v6, v2, v6
	v_add_u32_e32 v2, v2, v6
	s_waitcnt vmcnt(1)
	v_mul_hi_u32 v2, v1, v2
	v_mul_lo_u32 v6, v2, v0
	v_add_u32_e32 v7, 1, v1
	v_sub_u32_e32 v1, v1, v6
	v_add_u32_e32 v8, 1, v2
	v_cmp_ge_u32_e32 vcc, v1, v0
	v_sub_u32_e32 v6, v1, v0
	s_nop 0
	v_cndmask_b32_e32 v2, v2, v8, vcc
	v_cndmask_b32_e32 v1, v1, v6, vcc
	v_add_u32_e32 v6, 1, v2
	v_cmp_ge_u32_e32 vcc, v1, v0
	s_nop 1
	v_cndmask_b32_e32 v6, v2, v6, vcc
	v_mad_u64_u32 v[0:1], s[2:3], v0, v6, v[0:1]
	v_cmp_ne_u32_e32 vcc, v7, v0
	s_and_saveexec_b64 s[2:3], vcc
	s_xor_b64 s[2:3], exec, s[2:3]
	s_cbranch_execz .LBB0_201
	v_readlane_b32 s4, v249, 48
	v_add_u32_e32 v2, 0x900, v4
	v_readlane_b32 s5, v249, 49
	s_nop 1
	v_lshl_add_u64 v[0:1], v[2:3], 2, s[4:5]
	global_load_dword v2, v[0:1], off sc1
	s_waitcnt vmcnt(0)
	v_cmp_eq_u32_e32 vcc, v2, v6
	s_and_saveexec_b64 s[4:5], vcc
	s_cbranch_execz .LBB0_200
	s_add_u32 s6, s54, 0x329d8800
	s_addc_u32 s7, s55, 0
	s_mov_b32 s18, 1
	s_mov_b64 s[8:9], 0
	v_mov_b32_e32 v2, 0
	s_branch .LBB0_191

; DI unsigned xb_add(unsigned* p, unsigned v) { return __hip_atomic_fetch_add(p, v, __ATOMIC_RELAXED, __HIP_MEMORY_SCOPE_AGENT); }
; DI void xcd_barrier(const XcdBarrier& b) {
;     ...
;     unsigned long long ba_ = (unsigned long long)b.bar; unsigned bx = b.x; asm volatile("" : "+v"(bx));
;     unsigned* bar = (unsigned*)ba_;
;     __builtin_amdgcn_s_waitcnt(0);
;     unsigned nloc = b.st[0], nx = b.st[1];
;     if (nloc == 0u) { xcd_barrier_complete(bar, bx, nloc, nx); b.st[0] = nloc; b.st[1] = nx; }
;     const unsigned old = xb_add(&bar[XB_XSUB(bx)], 1u);
;     const unsigned gen = old / nloc;
;     if (old + 1u == (gen + 1u) * nloc) {
.LBB0_704:
	v_lshlrev_b32_e32 v8, 6, v0
	v_readlane_b32 s2, v249, 48
	v_add_u32_e32 v0, 0x500, v8
	v_readlane_b32 s3, v249, 49
	s_nop 1
	v_lshl_add_u64 v[4:5], v[0:1], 2, s[2:3]
	v_mov_b32_e32 v0, 1
	global_atomic_add v0, v[4:5], v0, off sc0
	buffer_inv sc1
	v_cvt_f32_u32_e32 v4, v2
	v_sub_u32_e32 v5, 0, v2
	v_rcp_iflag_f32_e32 v4, v4
	s_nop 0
	v_mul_f32_e32 v4, 0x4f7ffffe, v4
	v_cvt_u32_f32_e32 v4, v4
	v_mul_lo_u32 v5, v5, v4
	v_mul_hi_u32 v5, v4, v5
	v_add_u32_e32 v4, v4, v5
	s_waitcnt vmcnt(1)
	v_mul_hi_u32 v4, v0, v4
	v_mul_lo_u32 v5, v4, v2
	v_sub_u32_e32 v5, v0, v5
	v_cmp_ge_u32_e32 vcc, v5, v2
	v_add_u32_e32 v6, 1, v4
	v_add_u32_e32 v0, 1, v0
	v_cndmask_b32_e32 v4, v4, v6, vcc
	v_sub_u32_e32 v6, v5, v2
	v_cndmask_b32_e32 v5, v5, v6, vcc
	v_cmp_ge_u32_e32 vcc, v5, v2
	v_add_u32_e32 v5, 1, v4
	s_nop 0
	v_cndmask_b32_e32 v4, v4, v5, vcc
	s_waitcnt lgkmcnt(0)
	v_mad_u64_u32 v[6:7], s[2:3], v2, v4, v[2:3]
	v_cmp_ne_u32_e32 vcc, v0, v6
	v_add_u32_e32 v0, 0x900, v8
	s_and_saveexec_b64 s[2:3], vcc
	s_xor_b64 s[2:3], exec, s[2:3]
	s_cbranch_execz .LBB0_718
	v_readlane_b32 s4, v249, 48
	v_readlane_b32 s5, v249, 49
	s_nop 1
	v_lshl_add_u64 v[2:3], v[0:1], 2, s[4:5]
	global_load_dword v0, v[2:3], off sc1
	s_waitcnt vmcnt(0)
	v_cmp_eq_u32_e32 vcc, v0, v4
	s_and_saveexec_b64 s[4:5], vcc
	s_cbranch_execz .LBB0_717
	s_mov_b32 s16, 1
	s_mov_b64 s[6:7], 0
	s_branch .LBB0_708

; DI unsigned xb_add(unsigned* p, unsigned v) { return __hip_atomic_fetch_add(p, v, __ATOMIC_RELAXED, __HIP_MEMORY_SCOPE_AGENT); }
; DI void xcd_barrier(const XcdBarrier& b) {
;     ...
;     unsigned long long ba_ = (unsigned long long)b.bar; unsigned bx = b.x; asm volatile("" : "+v"(bx));
;     unsigned* bar = (unsigned*)ba_;
;     __builtin_amdgcn_s_waitcnt(0);
;     unsigned nloc = b.st[0], nx = b.st[1];
;     if (nloc == 0u) { xcd_barrier_complete(bar, bx, nloc, nx); b.st[0] = nloc; b.st[1] = nx; }
;     const unsigned old = xb_add(&bar[XB_XSUB(bx)], 1u);
;     const unsigned gen = old / nloc;
;     if (old + 1u == (gen + 1u) * nloc) {
.LBB0_1623:
	v_lshlrev_b32_e32 v8, 6, v0
	v_readlane_b32 s2, v249, 48
	v_add_u32_e32 v0, 0x500, v8
	v_readlane_b32 s3, v249, 49
	s_nop 1
	v_lshl_add_u64 v[4:5], v[0:1], 2, s[2:3]
	v_mov_b32_e32 v0, 1
	global_atomic_add v0, v[4:5], v0, off sc0
	buffer_inv sc1
	v_cvt_f32_u32_e32 v4, v2
	v_sub_u32_e32 v5, 0, v2
	v_rcp_iflag_f32_e32 v4, v4
	s_nop 0
	v_mul_f32_e32 v4, 0x4f7ffffe, v4
	v_cvt_u32_f32_e32 v4, v4
	v_mul_lo_u32 v5, v5, v4
	v_mul_hi_u32 v5, v4, v5
	v_add_u32_e32 v4, v4, v5
	s_waitcnt vmcnt(1)
	v_mul_hi_u32 v4, v0, v4
	v_mul_lo_u32 v5, v4, v2
	v_sub_u32_e32 v5, v0, v5
	v_cmp_ge_u32_e32 vcc, v5, v2
	v_add_u32_e32 v6, 1, v4
	v_add_u32_e32 v0, 1, v0
	v_cndmask_b32_e32 v4, v4, v6, vcc
	v_sub_u32_e32 v6, v5, v2
	v_cndmask_b32_e32 v5, v5, v6, vcc
	v_cmp_ge_u32_e32 vcc, v5, v2
	v_add_u32_e32 v5, 1, v4
	s_nop 0
	v_cndmask_b32_e32 v4, v4, v5, vcc
	s_waitcnt lgkmcnt(0)
	v_mad_u64_u32 v[6:7], s[2:3], v2, v4, v[2:3]
	v_cmp_ne_u32_e32 vcc, v0, v6
	v_add_u32_e32 v0, 0x900, v8
	s_and_saveexec_b64 s[2:3], vcc
	s_xor_b64 s[2:3], exec, s[2:3]
	s_cbranch_execz .LBB0_1637
	v_readlane_b32 s4, v249, 48
	v_readlane_b32 s5, v249, 49
	s_nop 1
	v_lshl_add_u64 v[2:3], v[0:1], 2, s[4:5]
	global_load_dword v0, v[2:3], off sc1
	s_waitcnt vmcnt(0)
	v_cmp_eq_u32_e32 vcc, v0, v4
	s_and_saveexec_b64 s[4:5], vcc
	s_cbranch_execz .LBB0_1636
	s_mov_b32 s18, 1
	s_mov_b64 s[8:9], 0
	s_branch .LBB0_1627
